# P0 x copy: next row requested one iteration ahead into a second register set (its HBM latency overlaps this row's stores and the 6-hop reduction); only the previous row's stores stay in flight at the
# baseline (speedup 1.0000x reference)
; __global__ void __launch_bounds__(512) mega(Params p) {
;     ...
;       const int lane = tid & 63, wave = tid >> 6;
;       float* ssB = (float*)(ws + WS_SS) + (size_t)T * 16;
;       for (int row = bid * 8 + wave; row < T; row += nblk * 8) {
;         const float* r = p.in[0] + (size_t)row * DM; float ss = 0.f;
.LBB0_195:
	v_ashrrev_i32_e32 v6, 6, v2
	s_lshl_b32 s0, s76, 3
	v_add_u32_e32 v7, s0, v6
	s_mov_b32 s2, 0x8000
	v_cmp_gt_i32_e32 vcc, s2, v7
	s_and_saveexec_b64 s[2:3], vcc
	s_cbranch_execz .LBB0_200
	s_load_dwordx4 s[8:11], s[78:79], 0xa0
	v_add_u32_e32 v14, 0xfffff800, v7
	v_ashrrev_i32_e32 v7, 31, v6
	s_ashr_i32 s1, s0, 31
	v_and_b32_e32 v12, 63, v10
	v_lshl_add_u64 v[10:11], v[6:7], 0, s[0:1]
	s_load_dwordx16 s[12:27], s[78:79], 0x0
	v_lshlrev_b32_e32 v4, 2, v12
	v_mov_b32_e32 v5, 0
	v_lshlrev_b64 v[6:7], 6, v[10:11]
	v_lshl_add_u64 v[6:7], v[6:7], 0, v[4:5]
	v_lshlrev_b64 v[8:9], 11, v[10:11]
	s_waitcnt lgkmcnt(0)
	v_lshl_add_u64 v[6:7], s[10:11], 0, v[6:7]
	s_mov_b64 s[6:7], 0x1f800000
	v_lshl_or_b32 v8, v12, 3, v8
	v_xor_b32_e32 v3, 0x80, v4
	v_cmp_gt_u32_e32 vcc, 16, v12
	v_cmp_eq_u32_e64 s[4:5], 0, v12
	v_lshl_add_u64 v[6:7], v[6:7], 0, s[6:7]
	v_lshl_add_u64 v[8:9], s[10:11], 0, v[8:9]
	s_mov_b64 s[6:7], 0x10000400
	v_lshlrev_b32_e32 v4, 4, v12
	v_lshlrev_b64 v[12:13], 12, v[10:11]
	v_lshl_add_u64 v[8:9], v[8:9], 0, s[6:7]
	v_lshl_add_u64 v[10:11], s[12:13], 0, v[12:13]
	v_lshl_add_u64 v[12:13], s[8:9], 0, v[12:13]
	s_mov_b64 s[8:9], 0
	s_mov_b64 s[10:11], 0x20000
	s_mov_b64 s[12:13], 0x400000
	s_mov_b64 s[14:15], 0x800000
	s_movk_i32 s16, 0x77ff
	v_lshl_add_u64 v[28:29], v[10:11], 0, v[4:5]
	global_load_dwordx4 v[128:131], v[28:29], off
	global_load_dwordx4 v[132:135], v[28:29], off offset:1024
	global_load_dwordx4 v[136:139], v[28:29], off offset:2048
	global_load_dwordx4 v[140:143], v[28:29], off offset:3072
	s_waitcnt vmcnt(0)
	s_branch .LBB0_198

; DEVI unsigned pk2(float lo, float hi) { unsigned r; asm("v_cvt_pk_bf16_f32 %0, %1, %2" : "=v"(r) : "v"(lo), "v"(hi)); return r; }
; template <int M> DEVI float shx(float v) { return __int_as_float(__builtin_amdgcn_ds_swizzle(__float_as_int(v), (M << 10) | 0x1f)); }
; DEVI float shx32(float v, int lane) { return __int_as_float(__builtin_amdgcn_ds_bpermute((lane ^ 32) << 2, __float_as_int(v))); }
; __global__ void __launch_bounds__(512) mega(Params p) {
;     ...
;       for (int row = bid * 8 + wave; row < T; row += nblk * 8) {
;         const float* r = p.in[0] + (size_t)row * DM; float ss = 0.f;
; #pragma unroll
;         for (int j = 0; j < 4; ++j) {
;           const float4 v = *(const float4*)(r + j * 256 + lane * 4);
;           *(float4*)(xf + (size_t)row * DM + j * 256 + lane * 4) = v;
;           u32x2 w; w.x = pk2(v.x, v.y); w.y = pk2(v.z, v.w);
;           *(u32x2*)(cx.xb + (size_t)row * DM + j * 256 + lane * 4) = w;
;           ss += v.x * v.x + v.y * v.y + v.z * v.z + v.w * v.w;
;         }
;         ss += shx32(ss, lane); ss += shx<16>(ss); ss += shx<8>(ss); ss += shx<4>(ss); ss += shx<2>(ss); ss += shx<1>(ss);
;         if (lane < 16) ssB[(size_t)row * 16 + lane] = lane == 0 ? ss : 0.f;
.LBB0_198:
	s_waitcnt vmcnt(9)
	v_mov_b32_e32 v16, v128
	v_mov_b32_e32 v17, v129
	v_mov_b32_e32 v18, v130
	v_mov_b32_e32 v19, v131
	v_mov_b32_e32 v20, v132
	v_mov_b32_e32 v21, v133
	v_mov_b32_e32 v22, v134
	v_mov_b32_e32 v23, v135
	v_mov_b32_e32 v24, v136
	v_mov_b32_e32 v25, v137
	v_mov_b32_e32 v26, v138
	v_mov_b32_e32 v27, v139
	v_mov_b32_e32 v110, v140
	v_mov_b32_e32 v111, v141
	v_mov_b32_e32 v112, v142
	v_mov_b32_e32 v113, v143
	v_add_u32_e32 v28, 0x800, v14
	v_cmp_ge_i32_e64 s[56:57], s16, v28
	s_and_saveexec_b64 s[58:59], s[56:57]
	s_cbranch_execz .Lxc_nopf
	v_lshl_add_u64 v[28:29], v[10:11], 0, v[4:5]
	v_lshl_add_u64 v[28:29], v[28:29], 0, s[14:15]
	global_load_dwordx4 v[128:131], v[28:29], off
	global_load_dwordx4 v[132:135], v[28:29], off offset:1024
	global_load_dwordx4 v[136:139], v[28:29], off offset:2048
	global_load_dwordx4 v[140:143], v[28:29], off offset:3072
.Lxc_nopf:
	s_mov_b64 exec, s[58:59]
	v_lshl_add_u64 v[32:33], v[12:13], 0, v[4:5]
	v_cvt_pk_bf16_f32 v120, v16, v17
	v_cvt_pk_bf16_f32 v121, v18, v19
	v_pk_mul_f32 v[116:117], v[16:17], v[16:17]
	v_pk_mul_f32 v[118:119], v[18:19], v[18:19]
	global_store_dwordx4 v[32:33], v[16:19], off
	global_store_dwordx2 v[8:9], v[120:121], off offset:-1024
	v_add_f32_e32 v15, v116, v117
	v_add_f32_e32 v15, v15, v118
	v_add_f32_e32 v15, v15, v119
	v_cvt_pk_bf16_f32 v122, v20, v21
	v_cvt_pk_bf16_f32 v123, v22, v23
	v_pk_mul_f32 v[116:117], v[20:21], v[20:21]
	v_pk_mul_f32 v[118:119], v[22:23], v[22:23]
	global_store_dwordx4 v[32:33], v[20:23], off offset:1024
	global_store_dwordx2 v[8:9], v[122:123], off offset:-512
	v_add_f32_e32 v116, v116, v117
	v_add_f32_e32 v116, v116, v118
	v_add_f32_e32 v116, v116, v119
	v_add_f32_e32 v15, v15, v116
	v_cvt_pk_bf16_f32 v124, v24, v25
	v_cvt_pk_bf16_f32 v125, v26, v27
	v_pk_mul_f32 v[116:117], v[24:25], v[24:25]
	v_pk_mul_f32 v[118:119], v[26:27], v[26:27]
	global_store_dwordx4 v[32:33], v[24:27], off offset:2048
	global_store_dwordx2 v[8:9], v[124:125], off
	v_add_f32_e32 v116, v116, v117
	v_add_f32_e32 v116, v116, v118
	v_add_f32_e32 v116, v116, v119
	v_add_f32_e32 v15, v15, v116
	v_cvt_pk_bf16_f32 v126, v110, v111
	v_cvt_pk_bf16_f32 v127, v112, v113
	v_pk_mul_f32 v[116:117], v[110:111], v[110:111]
	v_pk_mul_f32 v[118:119], v[112:113], v[112:113]
	global_store_dwordx4 v[32:33], v[110:113], off offset:3072
	global_store_dwordx2 v[8:9], v[126:127], off offset:512
	v_add_f32_e32 v116, v116, v117
	v_add_f32_e32 v116, v116, v118
	v_add_f32_e32 v116, v116, v119
	v_add_f32_e32 v15, v15, v116
	ds_bpermute_b32 v16, v3, v15
	s_waitcnt lgkmcnt(0)
	v_add_f32_e32 v15, v15, v16
	ds_swizzle_b32 v16, v15 offset:swizzle(SWAP,16)
	s_waitcnt lgkmcnt(0)
	v_add_f32_e32 v15, v15, v16
	ds_swizzle_b32 v16, v15 offset:swizzle(SWAP,8)
	s_waitcnt lgkmcnt(0)
	v_add_f32_e32 v15, v15, v16
	ds_swizzle_b32 v16, v15 offset:swizzle(SWAP,4)
	s_waitcnt lgkmcnt(0)
	v_add_f32_e32 v15, v15, v16
	ds_swizzle_b32 v16, v15 offset:swizzle(SWAP,2)
	s_waitcnt lgkmcnt(0)
	v_add_f32_e32 v15, v15, v16
	ds_swizzle_b32 v16, v15 offset:swizzle(SWAP,1)
	s_and_saveexec_b64 s[6:7], vcc
	s_cbranch_execz .LBB0_197
	s_waitcnt lgkmcnt(0)
	v_add_f32_e32 v15, v15, v16
	v_cndmask_b32_e64 v15, 0, v15, s[4:5]
	global_store_dword v[6:7], v15, off
	s_branch .LBB0_197
